# v24 + selected-loop interior tile: ALiBi key offsets enter the QK MFMA chains as C operand (no per-tile v_add), softmax in place
# baseline (speedup 1.0000x reference)
.LBB0_876:
	v_and_b32_e32 v3, 64, v228
	v_xor_b32_e32 v2, 32, v228
	v_add_u32_e32 v3, 64, v3
	v_cmp_lt_i32_e32 vcc, v2, v3
	v_add_f32_e32 v0, 1.0, v122
	v_rcp_f32_e32 v0, v0
	v_cndmask_b32_e32 v2, v228, v2, vcc
	v_lshlrev_b32_e32 v186, 2, v2
	ds_bpermute_b32 v2, v186, v127
	s_bcnt1_i32_b64 s10, s[10:11]
	s_bcnt1_i32_b64 s11, s[14:15]
	s_add_i32 s22, s11, s10
	s_bcnt1_i32_b64 s10, s[16:17]
	s_waitcnt lgkmcnt(0)
	v_add_f32_e32 v2, v127, v2
	v_div_scale_f32 v3, s[14:15], v2, v2, v0
	v_rcp_f32_e32 v4, v3
	s_add_i32 s22, s22, s10
	v_cmp_lt_f32_e64 s[10:11], 0, v2
	s_cmp_lg_u32 s22, 0
	v_fma_f32 v5, -v3, v4, 1.0
	v_fmac_f32_e32 v4, v5, v4
	v_div_scale_f32 v5, vcc, v0, v2, v0
	v_mul_f32_e32 v6, v5, v4
	v_fma_f32 v7, -v3, v6, v5
	v_fmac_f32_e32 v6, v7, v4
	v_fma_f32 v3, -v3, v6, v5
	v_div_fmas_f32 v3, v3, v4, v6
	v_div_fixup_f32 v0, v3, v2, v0
	ds_read2st64_b32 v[2:3], v183 offset1:1
	ds_read2st64_b32 v[122:123], v183 offset0:14 offset1:15
	v_cndmask_b32_e64 v0, 0, v0, s[10:11]
	s_waitcnt lgkmcnt(1)
	v_fma_f32 v2, v34, v0, v2
	v_fmac_f32_e32 v3, v35, v0
	ds_write2st64_b32 v183, v2, v3 offset1:1
	ds_read2st64_b32 v[2:3], v183 offset0:2 offset1:3
	s_waitcnt lgkmcnt(2)
	v_fma_f32 v122, v48, v0, v122
	v_fmac_f32_e32 v123, v49, v0
	ds_write2st64_b32 v183, v122, v123 offset0:14 offset1:15
	s_waitcnt lgkmcnt(1)
	v_fma_f32 v2, v36, v0, v2
	v_fmac_f32_e32 v3, v37, v0
	ds_write2st64_b32 v183, v2, v3 offset0:2 offset1:3
	ds_read2st64_b32 v[2:3], v183 offset0:4 offset1:5
	s_waitcnt lgkmcnt(0)
	v_fma_f32 v2, v38, v0, v2
	v_fmac_f32_e32 v3, v39, v0
	ds_write2st64_b32 v183, v2, v3 offset0:4 offset1:5
	ds_read2st64_b32 v[2:3], v183 offset0:6 offset1:7
	s_waitcnt lgkmcnt(0)
	v_fma_f32 v2, v40, v0, v2
	v_fmac_f32_e32 v3, v41, v0
	ds_write2st64_b32 v183, v2, v3 offset0:6 offset1:7
	ds_read2st64_b32 v[2:3], v183 offset0:8 offset1:9
	s_waitcnt lgkmcnt(0)
	v_fma_f32 v2, v42, v0, v2
	v_fmac_f32_e32 v3, v43, v0
	ds_write2st64_b32 v183, v2, v3 offset0:8 offset1:9
	ds_read2st64_b32 v[2:3], v183 offset0:10 offset1:11
	s_waitcnt lgkmcnt(0)
	v_fma_f32 v2, v44, v0, v2
	v_fmac_f32_e32 v3, v45, v0
	ds_write2st64_b32 v183, v2, v3 offset0:10 offset1:11
	ds_read2st64_b32 v[2:3], v183 offset0:12 offset1:13
	s_waitcnt lgkmcnt(0)
	v_fma_f32 v2, v46, v0, v2
	v_fmac_f32_e32 v3, v47, v0
	ds_write2st64_b32 v183, v2, v3 offset0:12 offset1:13
	ds_read2st64_b32 v[2:3], v183 offset0:16 offset1:17
	s_waitcnt lgkmcnt(0)
	v_pk_fma_f32 v[124:125], v[50:51], v[0:1], v[2:3] op_sel_hi:[1,0,1]
	ds_read2st64_b32 v[2:3], v183 offset0:18 offset1:19
	ds_write2st64_b32 v183, v124, v125 offset0:16 offset1:17
	s_waitcnt lgkmcnt(1)
	v_pk_fma_f32 v[126:127], v[52:53], v[0:1], v[2:3] op_sel_hi:[1,0,1]
	ds_read2st64_b32 v[2:3], v183 offset0:20 offset1:21
	ds_write2st64_b32 v183, v126, v127 offset0:18 offset1:19
	s_waitcnt lgkmcnt(1)
	v_pk_fma_f32 v[128:129], v[54:55], v[0:1], v[2:3] op_sel_hi:[1,0,1]
	ds_read2st64_b32 v[2:3], v183 offset0:22 offset1:23
	ds_write2st64_b32 v183, v128, v129 offset0:20 offset1:21
	s_waitcnt lgkmcnt(1)
	v_pk_fma_f32 v[130:131], v[56:57], v[0:1], v[2:3] op_sel_hi:[1,0,1]
	ds_read2st64_b32 v[2:3], v183 offset0:24 offset1:25
	ds_write2st64_b32 v183, v130, v131 offset0:22 offset1:23
	s_waitcnt lgkmcnt(1)
	v_pk_fma_f32 v[132:133], v[58:59], v[0:1], v[2:3] op_sel_hi:[1,0,1]
	ds_read2st64_b32 v[2:3], v183 offset0:26 offset1:27
	ds_write2st64_b32 v183, v132, v133 offset0:24 offset1:25
	s_waitcnt lgkmcnt(1)
	v_pk_fma_f32 v[134:135], v[60:61], v[0:1], v[2:3] op_sel_hi:[1,0,1]
	ds_read2st64_b32 v[2:3], v183 offset0:28 offset1:29
	ds_write2st64_b32 v183, v134, v135 offset0:26 offset1:27
	s_waitcnt lgkmcnt(1)
	v_pk_fma_f32 v[136:137], v[62:63], v[0:1], v[2:3] op_sel_hi:[1,0,1]
	ds_read2st64_b32 v[2:3], v183 offset0:30 offset1:31
	ds_write2st64_b32 v183, v136, v137 offset0:28 offset1:29
	s_waitcnt lgkmcnt(1)
	v_pk_fma_f32 v[138:139], v[64:65], v[0:1], v[2:3] op_sel_hi:[1,0,1]
	ds_write2st64_b32 v183, v138, v139 offset0:30 offset1:31
	s_cbranch_scc0 .LBB0_993
	s_cmp_lt_i32 s30, 0
	s_cselect_b32 s30, s21, s30
	s_lshl_b32 s2, s2, 23
	s_add_u32 s2, s42, s2
	s_addc_u32 s10, s43, 0
	s_add_u32 s2, s2, s3
	s_addc_u32 s3, s10, 0
	s_add_u32 s14, s2, 0x8300400
	s_addc_u32 s15, s3, 0
	v_mov_b32_e32 v2, v1
	v_mov_b32_e32 v3, v1
	v_mov_b32_e32 v4, v1
	v_mov_b32_e32 v5, v1
	v_mov_b32_e32 v6, v1
	v_mov_b32_e32 v7, v1
	v_mov_b32_e32 v8, v1
	v_mov_b32_e32 v9, v1
	v_mov_b32_e32 v10, v1
	v_mov_b32_e32 v11, v1
	v_mov_b32_e32 v12, v1
	v_mov_b32_e32 v13, v1
	v_mov_b32_e32 v14, v1
	v_mov_b32_e32 v15, v1
	v_mov_b32_e32 v16, v1
	v_mov_b32_e32 v17, v1
	v_mov_b32_e32 v18, v1
	v_mov_b32_e32 v19, v1
	v_mov_b32_e32 v20, v1
	v_mov_b32_e32 v21, v1
	v_mov_b32_e32 v22, v1
	v_mov_b32_e32 v23, v1
	v_mov_b32_e32 v24, v1
	v_mov_b32_e32 v25, v1
	v_mov_b32_e32 v26, v1
	v_mov_b32_e32 v27, v1
	v_mov_b32_e32 v28, v1
	v_mov_b32_e32 v29, v1
	v_mov_b32_e32 v30, v1
	v_mov_b32_e32 v31, v1
	s_add_u32 s16, s2, 0x8300600
	v_mov_b32_e32 v0, v1
	v_mov_b64_e32 v[32:33], v[30:31]
	s_mov_b32 s23, 0
	v_or_b32_e32 v187, s25, v185
	v_mad_u32_u24 v185, v185, 24, 0
	s_addc_u32 s17, s3, 0
	v_mov_b32_e32 v189, 0xf149f2ca
	v_mov_b32_e32 v188, 0
	v_mov_b64_e32 v[30:31], v[28:29]
	v_mov_b64_e32 v[28:29], v[26:27]
	v_mov_b64_e32 v[26:27], v[24:25]
	v_mov_b64_e32 v[24:25], v[22:23]
	v_mov_b64_e32 v[22:23], v[20:21]
	v_mov_b64_e32 v[20:21], v[18:19]
	v_mov_b64_e32 v[18:19], v[16:17]
	v_mov_b64_e32 v[16:17], v[14:15]
	v_mov_b64_e32 v[14:15], v[12:13]
	v_mov_b64_e32 v[12:13], v[10:11]
	v_mov_b64_e32 v[10:11], v[8:9]
	v_mov_b64_e32 v[8:9], v[6:7]
	v_mov_b64_e32 v[6:7], v[4:5]
	v_mov_b64_e32 v[4:5], v[2:3]
	v_mov_b64_e32 v[2:3], v[0:1]
	v_mov_b32_e32 v194, v148
	v_mov_b32_e32 v195, v118
	v_mov_b32_e32 v196, v149
	v_mov_b32_e32 v197, v150
	v_mov_b32_e32 v198, v151
	v_mov_b32_e32 v199, v152
	v_mov_b32_e32 v200, v153
	v_mov_b32_e32 v201, v154
	v_mov_b32_e32 v202, v155
	v_mov_b32_e32 v203, v156
	v_mov_b32_e32 v204, v157
	v_mov_b32_e32 v205, v158
	v_mov_b32_e32 v206, v159
	v_mov_b32_e32 v207, v160
	v_mov_b32_e32 v208, v161
	v_mov_b32_e32 v209, v162
	v_mov_b32_e32 v210, v163
	v_mov_b32_e32 v211, v166
	v_mov_b32_e32 v212, v167
	v_mov_b32_e32 v213, v168
	v_mov_b32_e32 v214, v169
	v_mov_b32_e32 v215, v170
	v_mov_b32_e32 v216, v171
	v_mov_b32_e32 v217, v172
	v_mov_b32_e32 v218, v173
	v_mov_b32_e32 v219, v174
	v_mov_b32_e32 v220, v175
	v_mov_b32_e32 v221, v176
	v_mov_b32_e32 v222, v177
	v_mov_b32_e32 v223, v178
	v_mov_b32_e32 v224, v179
	v_mov_b32_e32 v225, v180
.LBB0_878:
	v_mov_b32_e32 v0, v165
	s_lshl_b32 s2, s30, 6
	v_ashrrev_i32_e32 v34, 3, v0
	v_add_u32_e32 v34, s2, v34
	v_ashrrev_i32_e32 v35, 31, v34
	v_lshlrev_b64 v[34:35], 11, v[34:35]
	v_lshlrev_b32_e32 v0, 4, v0
	v_lshl_add_u64 v[34:35], s[14:15], 0, v[34:35]
	v_and_b32_e32 v0, 0x70, v0
	v_lshl_add_u64 v[34:35], v[34:35], 0, v[0:1]
	v_mov_b32_e32 v0, v165
	global_load_dwordx4 v[90:93], v[34:35], off
	s_nop 0
	v_ashrrev_i32_e32 v34, 3, v0
	v_add_u32_e32 v34, s2, v34
	v_ashrrev_i32_e32 v35, 31, v34
	v_lshlrev_b64 v[34:35], 11, v[34:35]
	v_lshlrev_b32_e32 v0, 4, v0
	v_lshl_add_u64 v[34:35], s[16:17], 0, v[34:35]
	v_and_b32_e32 v0, 0x70, v0
	v_lshl_add_u64 v[34:35], v[34:35], 0, v[0:1]
	global_load_dwordx4 v[94:97], v[34:35], off
	s_ashr_i32 s2, s67, 6
	v_lshl_add_u32 v0, s2, 3, v185
	ds_read_b64 v[34:35], v0 offset:59904
	s_waitcnt lgkmcnt(0)
	v_lshrrev_b64 v[34:35], s67, v[34:35]
	v_and_b32_e32 v0, 1, v34
	v_cmp_eq_u32_e64 s[10:11], 1, v0
	v_cmp_ne_u32_e32 vcc, 0, v0
	s_cbranch_vccz .LBB0_888
	s_lshl_b32 s3, s67, 6
	s_or_b32 s2, s3, 63
	s_cmp_gt_i32 s2, s25
	s_mul_i32 s2, s64, 0x2400
	v_add_u32_e32 v192, s2, v184
	ds_read_b128 v[98:101], v192
	ds_read_b128 v[102:105], v192 offset:32
	ds_read_b128 v[106:109], v192 offset:64
	ds_read_b128 v[110:113], v192 offset:96
	v_add_u32_e32 v0, s3, v120
	s_mul_i32 s2, s64, 0x3000
	s_mov_b64 s[18:19], -1
	v_sub_u32_e32 v190, v187, v0
	s_cbranch_scc1 .LBB0_883
	s_waitcnt lgkmcnt(3)
	v_mfma_f32_32x32x16_bf16 v[50:65], v[98:101], v[66:69], v[194:209]
	ds_read_b128 v[34:37], v192 offset:4608
	ds_read_b128 v[232:235], v192 offset:4640
	v_mov_b32_e32 v0, v190
	v_mov_b32_e32 v229, v188
	s_waitcnt lgkmcnt(1)
	v_mfma_f32_32x32x16_bf16 v[34:49], v[34:37], v[66:69], v[210:225]
	v_mfma_f32_32x32x16_bf16 v[50:65], v[102:105], v[70:73], v[50:65]
	s_waitcnt lgkmcnt(0)
	v_mfma_f32_32x32x16_bf16 v[34:49], v[232:235], v[70:73], v[34:49]
	ds_read_b128 v[232:235], v192 offset:4672
	v_mfma_f32_32x32x16_bf16 v[50:65], v[106:109], v[74:77], v[50:65]
	s_waitcnt lgkmcnt(0)
	v_mfma_f32_32x32x16_bf16 v[34:49], v[232:235], v[74:77], v[34:49]
	ds_read_b128 v[232:235], v192 offset:4704
	s_nop 0
	v_cvt_f32_i32_e32 v231, v0
	v_mfma_f32_32x32x16_bf16 v[50:65], v[110:113], v[78:81], v[50:65]
	s_waitcnt lgkmcnt(0)
	v_mfma_f32_32x32x16_bf16 v[34:49], v[232:235], v[78:81], v[34:49]
	s_nop 9
	v_max3_f32 v0, v50, s28, v51
	v_max3_f32 v0, v0, v52, v53
	v_max3_f32 v0, v0, v54, v55
	v_max3_f32 v0, v0, v56, v57
	v_max3_f32 v0, v0, v58, v59
	v_max3_f32 v0, v0, v60, v61
	v_max3_f32 v0, v0, v62, v63
	v_max3_f32 v0, v0, v64, v65
	v_max3_f32 v0, v0, v34, v35
	v_max3_f32 v0, v0, v36, v37
	v_max3_f32 v0, v0, v38, v39
	v_max3_f32 v0, v0, v40, v41
	v_max3_f32 v0, v0, v42, v43
	v_max3_f32 v0, v0, v44, v45
	v_max3_f32 v0, v0, v46, v47
	v_max3_f32 v0, v0, v48, v49
	v_fma_f32 v0, -v118, v231, v0
	v_cndmask_b32_e64 v0, v144, v0, s[10:11]
	ds_bpermute_b32 v230, v186, v0
	s_waitcnt lgkmcnt(0)
	v_max3_f32 v0, v189, v0, v230
	v_cmp_gt_f32_e32 vcc, v0, v189
	s_cbranch_vccz .LBB0_882
	v_sub_f32_e32 v230, v189, v0
	v_exp_f32_e32 v230, v230
	s_nop 0
	v_mul_f32_e32 v229, v188, v230
	v_pk_mul_f32 v[32:33], v[32:33], v[230:231] op_sel_hi:[1,0]
	v_pk_mul_f32 v[30:31], v[30:31], v[230:231] op_sel_hi:[1,0]
	v_pk_mul_f32 v[28:29], v[28:29], v[230:231] op_sel_hi:[1,0]
	v_pk_mul_f32 v[26:27], v[26:27], v[230:231] op_sel_hi:[1,0]
	v_pk_mul_f32 v[24:25], v[24:25], v[230:231] op_sel_hi:[1,0]
	v_pk_mul_f32 v[22:23], v[22:23], v[230:231] op_sel_hi:[1,0]
	v_pk_mul_f32 v[20:21], v[20:21], v[230:231] op_sel_hi:[1,0]
	v_pk_mul_f32 v[18:19], v[18:19], v[230:231] op_sel_hi:[1,0]
	v_pk_mul_f32 v[16:17], v[16:17], v[230:231] op_sel_hi:[1,0]
	v_pk_mul_f32 v[14:15], v[14:15], v[230:231] op_sel_hi:[1,0]
	v_pk_mul_f32 v[12:13], v[12:13], v[230:231] op_sel_hi:[1,0]
	v_pk_mul_f32 v[10:11], v[10:11], v[230:231] op_sel_hi:[1,0]
	v_pk_mul_f32 v[8:9], v[8:9], v[230:231] op_sel_hi:[1,0]
	v_pk_mul_f32 v[6:7], v[6:7], v[230:231] op_sel_hi:[1,0]
	v_pk_mul_f32 v[4:5], v[4:5], v[230:231] op_sel_hi:[1,0]
	v_pk_mul_f32 v[2:3], v[2:3], v[230:231] op_sel_hi:[1,0]
.LBB0_882:
	v_mul_f32_e64 v231, -v118, v231
	v_sub_f32_e32 v231, v0, v231
	v_cndmask_b32_e64 v231, v146, v231, s[10:11]
	v_sub_f32_e32 v50, v50, v231
	v_exp_f32_e32 v50, v50
	v_sub_f32_e32 v51, v51, v231
	v_exp_f32_e32 v51, v51
	v_sub_f32_e32 v52, v52, v231
	v_exp_f32_e32 v52, v52
	v_sub_f32_e32 v53, v53, v231
	v_exp_f32_e32 v53, v53
	v_sub_f32_e32 v54, v54, v231
	v_exp_f32_e32 v54, v54
	v_sub_f32_e32 v55, v55, v231
	v_exp_f32_e32 v55, v55
	v_add_f32_e32 v191, v51, v50
	v_sub_f32_e32 v56, v56, v231
	v_exp_f32_e32 v56, v56
	v_add_f32_e32 v191, v52, v191
	v_sub_f32_e32 v57, v57, v231
	v_exp_f32_e32 v57, v57
	v_add_f32_e32 v191, v53, v191
	v_sub_f32_e32 v58, v58, v231
	v_exp_f32_e32 v58, v58
	v_add_f32_e32 v191, v54, v191
	v_sub_f32_e32 v59, v59, v231
	v_exp_f32_e32 v59, v59
	v_add_f32_e32 v191, v55, v191
	v_sub_f32_e32 v60, v60, v231
	v_exp_f32_e32 v60, v60
	v_add_f32_e32 v191, v56, v191
	v_sub_f32_e32 v61, v61, v231
	v_exp_f32_e32 v61, v61
	v_add_f32_e32 v191, v57, v191
	v_sub_f32_e32 v62, v62, v231
	v_exp_f32_e32 v62, v62
	v_add_f32_e32 v191, v58, v191
	v_sub_f32_e32 v63, v63, v231
	v_exp_f32_e32 v63, v63
	v_add_f32_e32 v191, v59, v191
	v_sub_f32_e32 v64, v64, v231
	v_exp_f32_e32 v64, v64
	v_add_f32_e32 v191, v60, v191
	v_sub_f32_e32 v65, v65, v231
	v_exp_f32_e32 v65, v65
	v_add_f32_e32 v191, v61, v191
	v_sub_f32_e32 v34, v34, v231
	v_exp_f32_e32 v34, v34
	v_add_f32_e32 v191, v62, v191
	v_sub_f32_e32 v35, v35, v231
	v_exp_f32_e32 v35, v35
	v_add_f32_e32 v191, v63, v191
	v_sub_f32_e32 v36, v36, v231
	v_exp_f32_e32 v36, v36
	v_add_f32_e32 v191, v64, v191
	v_sub_f32_e32 v37, v37, v231
	v_exp_f32_e32 v37, v37
	v_add_f32_e32 v191, v65, v191
	v_sub_f32_e32 v38, v38, v231
	v_exp_f32_e32 v38, v38
	v_add_f32_e32 v191, v34, v191
	v_sub_f32_e32 v39, v39, v231
	v_exp_f32_e32 v39, v39
	v_add_f32_e32 v191, v35, v191
	v_sub_f32_e32 v40, v40, v231
	v_exp_f32_e32 v40, v40
	v_add_f32_e32 v191, v36, v191
	v_sub_f32_e32 v41, v41, v231
	v_exp_f32_e32 v41, v41
	v_add_f32_e32 v191, v37, v191
	v_sub_f32_e32 v42, v42, v231
	v_exp_f32_e32 v42, v42
	v_add_f32_e32 v191, v38, v191
	v_sub_f32_e32 v43, v43, v231
	v_exp_f32_e32 v43, v43
	v_add_f32_e32 v191, v39, v191
	v_sub_f32_e32 v44, v44, v231
	v_exp_f32_e32 v44, v44
	v_add_f32_e32 v191, v40, v191
	v_sub_f32_e32 v45, v45, v231
	v_exp_f32_e32 v45, v45
	v_add_f32_e32 v191, v41, v191
	v_sub_f32_e32 v46, v46, v231
	v_exp_f32_e32 v46, v46
	v_add_f32_e32 v191, v42, v191
	v_sub_f32_e32 v47, v47, v231
	v_exp_f32_e32 v47, v47
	v_add_f32_e32 v191, v43, v191
	v_sub_f32_e32 v48, v48, v231
	v_exp_f32_e32 v48, v48
	v_add_f32_e32 v191, v44, v191
	v_sub_f32_e32 v49, v49, v231
	v_exp_f32_e32 v49, v49
	v_add_f32_e32 v191, v45, v191
	v_add_f32_e32 v191, v46, v191
	v_add_f32_e32 v191, v47, v191
	v_add_f32_e32 v191, v48, v191
	v_add_f32_e32 v191, v49, v191
	v_add_u32_e32 v236, s2, v182
	v_add_f32_e32 v191, v191, v229
	ds_read_b64_tr_b16 v[238:239], v236 offset:18432
	ds_read_b64_tr_b16 v[240:241], v236 offset:19200
	ds_read_b64_tr_b16 v[242:243], v236 offset:18496
	ds_read_b64_tr_b16 v[244:245], v236 offset:19264
	ds_read_b64_tr_b16 v[246:247], v236 offset:21504
	ds_read_b64_tr_b16 v[248:249], v236 offset:22272
	ds_read_b64_tr_b16 v[250:251], v236 offset:21568
	ds_read_b64_tr_b16 v[252:253], v236 offset:22336
	v_cvt_pk_bf16_f32 v232, v50, v51
	v_cvt_pk_bf16_f32 v233, v52, v53
	v_cvt_pk_bf16_f32 v234, v54, v55
	v_cvt_pk_bf16_f32 v235, v56, v57
	s_mov_b64 s[18:19], 0
	s_nop 0
	s_waitcnt lgkmcnt(6)
	v_mfma_f32_32x32x16_bf16 v[2:17], v[238:241], v[232:235], v[2:17]
	ds_read_b64_tr_b16 v[238:239], v236 offset:24576
	ds_read_b64_tr_b16 v[240:241], v236 offset:25344
	s_nop 0
	s_waitcnt lgkmcnt(6)
	v_mfma_f32_32x32x16_bf16 v[18:33], v[242:245], v[232:235], v[18:33]
	ds_read_b64_tr_b16 v[242:243], v236 offset:24640
	ds_read_b64_tr_b16 v[244:245], v236 offset:25408
	v_cvt_pk_bf16_f32 v232, v58, v59
	v_cvt_pk_bf16_f32 v233, v60, v61
	v_cvt_pk_bf16_f32 v234, v62, v63
	v_cvt_pk_bf16_f32 v235, v64, v65
	s_nop 0
	s_nop 0
	s_waitcnt lgkmcnt(6)
	v_mfma_f32_32x32x16_bf16 v[2:17], v[246:249], v[232:235], v[2:17]
	ds_read_b64_tr_b16 v[246:247], v236 offset:27648
	ds_read_b64_tr_b16 v[248:249], v236 offset:28416
	s_nop 0
	s_waitcnt lgkmcnt(6)
	v_mfma_f32_32x32x16_bf16 v[18:33], v[250:253], v[232:235], v[18:33]
	ds_read_b64_tr_b16 v[250:251], v236 offset:27712
	ds_read_b64_tr_b16 v[252:253], v236 offset:28480
	v_cvt_pk_bf16_f32 v232, v34, v35
	v_cvt_pk_bf16_f32 v233, v36, v37
	v_cvt_pk_bf16_f32 v234, v38, v39
	v_cvt_pk_bf16_f32 v235, v40, v41
	s_nop 0
	s_nop 0
	s_waitcnt lgkmcnt(6)
	v_mfma_f32_32x32x16_bf16 v[2:17], v[238:241], v[232:235], v[2:17]
	s_nop 0
	s_waitcnt lgkmcnt(4)
	v_mfma_f32_32x32x16_bf16 v[18:33], v[242:245], v[232:235], v[18:33]
	v_cvt_pk_bf16_f32 v232, v42, v43
	v_cvt_pk_bf16_f32 v233, v44, v45
	v_cvt_pk_bf16_f32 v234, v46, v47
	v_cvt_pk_bf16_f32 v235, v48, v49
	s_nop 0
	s_nop 0
	s_waitcnt lgkmcnt(2)
	v_mfma_f32_32x32x16_bf16 v[2:17], v[246:249], v[232:235], v[2:17]
	s_nop 0
	s_waitcnt lgkmcnt(0)
	v_mfma_f32_32x32x16_bf16 v[18:33], v[250:253], v[232:235], v[18:33]
	v_mov_b32_e32 v188, v191
	v_mov_b32_e32 v189, v0
	s_branch .LBB0_888
